# attention: first-half QK head K-fragment addresses also computed before the barrier
# baseline (speedup 1.0000x reference)
; #define LAS __attribute__((address_space(3)))
; __device__ __forceinline__ int v_rd_base(int lane) { return ((lane & 3) << 3) | (((lane >> 2) & 3) << 6) | (((lane >> 4) & 1) << 5) | (((lane >> 5) & 1) << 8); }
; #define WAIT_BAR() asm volatile("s_waitcnt vmcnt(0) lgkmcnt(0)\n\ts_barrier" ::: "memory")
; __device__ __forceinline__ void attn_unit(const bf16_t* __restrict__ Qb, const bf16_t* __restrict__ Kn, const bf16_t* __restrict__ Vh, const bf16_t* __restrict__ Kr,
;                                           bf16_t* __restrict__ Ob, int seq, char* lds, int wv_) { LAUNDER_IDS;
;     const int tid = tidx_, wid = __builtin_amdgcn_readfirstlane(tid >> 6), lane = tid & 63, r32 = lane & 31, hi = lane >> 5;
;     LAS unsigned char* lds3 = (LAS unsigned char*)lds;
;     float* ws = (float*)(lds + OFF_WS) + wid * 64; float* li_l = ws; float* al_l = ws + 32;
;     float m_reg = 0.f, l_reg = 0; f32x16 o[4] = {}; bf16x8 qr[12];
;     const bf16_t* Qw = Qb + (long)(wid * QBLK + r32) * LDQ + hi * 8;
; #pragma unroll
;     for (int d0 = 0; d0 < 12; ++d0) qr[d0] = *reinterpret_cast<const bf16x8*>(Qw + d0 * 16);
;     unsigned gkn[2], gv[2], gkr;
; #pragma unroll
;     for (int i = 0; i < 2; ++i) { const int c = wid * 2 + i; const int row = c * 4 + (lane >> 4), slot = lane & 15; gkn[i] = (unsigned)(row * (LDKV * 2) + ((slot ^ (row & 15)) << 4));
;         const int st = c * 2 + (lane >> 5), kk = (st >> 2) * 8 + ((lane & 31) >> 2), k = (kk & ~0xC) | ((kk & 4) << 1) | ((kk & 8) >> 1), col = (st & 3) * 32 + (lane & 3) * 8; gv[i] = (unsigned)(k * (LDKV * 2) + col * 2); }
;     { const int row = wid * 8 + (lane >> 3), slot = lane & 7; gkr = (unsigned)(row * 128 + ((slot ^ ((row >> 1) & 7)) << 4)); }
;     const int vb0 = (int)(uintptr_t)(lds + OFF_V) + v_rd_base(lane);
;     ...
;     f32x16 pA0, pA1, pB0, pB1; float mnA, mnB, alA, alB; bf16x8 pa0, pa1, pa2, pa3; const int NT = seq / KVBLK;
;     DMA(0, 0); DMA(1, 1); WAIT_BAR();
;     qkt(pA0, pA1, lds + OFF_K, qr, r32, hi); __builtin_amdgcn_s_setprio(0); partialSM<true>(pA0, pA1, m_reg, mnA, alA);
;     int s_prev = 0, s_cur = 1, s_next = 2;
.LBB0_215:
	s_and_b32 s5, s5, 0x3fffffc0
	s_lshl_b32 s5, s5, 2
	s_add_i32 s5, s5, 0
	s_add_i32 s5, s5, 0x1e000
	v_exp_f32_e32 v247, v0
	v_lshlrev_b32_e32 v0, 7, v24
	s_cmp_lg_u32 0, -1
	v_add3_u32 v174, s8, v0, v25
	v_add3_u32 v0, v17, v18, s14
	v_and_b32_e32 v22, 63, v22
	s_cselect_b32 s16, 0, 0
	v_lshl_or_b32 v0, v0, 13, v23
	s_lshl_b32 s13, s13, 16
	v_lshlrev_b32_e32 v27, 4, v22
	v_exp_f32_e32 v249, v1
	v_exp_f32_e32 v245, v2
	v_add_u32_e32 v0, v0, v20
	v_mov_b32_e32 v1, v161
	v_lshl_or_b32 v2, v16, 13, s13
	v_lshlrev_b32_e32 v26, 3, v22
	v_and_b32_e32 v27, 0xc0, v27
	v_lshlrev_b32_e32 v28, 1, v22
	v_exp_f32_e32 v248, v3
	v_exp_f32_e32 v244, v4
	v_exp_f32_e32 v246, v5
	v_exp_f32_e32 v242, v6
	v_exp_f32_e32 v243, v7
	v_exp_f32_e32 v239, v8
	v_exp_f32_e32 v241, v9
	v_exp_f32_e32 v238, v10
	v_exp_f32_e32 v240, v11
	v_exp_f32_e32 v235, v12
	v_exp_f32_e32 v237, v13
	v_exp_f32_e32 v234, v14
	v_exp_f32_e32 v236, v15
	v_lshl_add_u64 v[176:177], s[0:1], 0, v[0:1]
	v_or_b32_e32 v0, v2, v19
	s_mov_b32 s13, 0x8000
	v_and_or_b32 v27, v26, 24, v27
	v_and_b32_e32 v28, 32, v28
	v_and_b32_e32 v26, 0x100, v26
	v_lshl_add_u64 v[178:179], s[0:1], 0, v[0:1]
	v_or3_b32 v0, v2, v21, s13
	v_mov_b32_e32 v14, v161
	v_mov_b32_e32 v15, v161
	v_or3_b32 v204, v27, v28, v26
	s_add_i32 s16, s16, 0x12000
	v_cmp_gt_u32_e64 s[38:39], 32, v22
	v_lshl_add_u64 v[180:181], s[0:1], 0, v[0:1]
	v_mov_b32_e32 v0, v161
	v_mov_b32_e32 v2, v161
	v_mov_b32_e32 v3, v161
	v_mov_b32_e32 v4, v161
	v_mov_b32_e32 v5, v161
	v_mov_b32_e32 v6, v161
	v_mov_b32_e32 v7, v161
	v_mov_b32_e32 v8, v161
	v_mov_b32_e32 v9, v161
	v_mov_b32_e32 v10, v161
	v_mov_b32_e32 v11, v161
	v_mov_b32_e32 v12, v161
	v_mov_b32_e32 v13, v161
	v_mov_b64_e32 v[62:63], v[14:15]
	v_mov_b64_e32 v[46:47], v[14:15]
	v_mov_b64_e32 v[30:31], v[14:15]
	s_mov_b32 s9, 2
	s_mov_b32 s10, 1
	s_mov_b32 s11, -1
	s_mov_b32 s15, 0
	v_add_u32_e32 v205, s16, v204
	v_lshl_add_u32 v202, v183, 2, s5
	v_mov_b32_e32 v175, v161
	v_mov_b32_e32 v203, 0
	v_mov_b32_e32 v230, 1.0
	v_mov_b64_e32 v[60:61], v[12:13]
	v_mov_b64_e32 v[58:59], v[10:11]
	v_mov_b64_e32 v[56:57], v[8:9]
	v_mov_b64_e32 v[54:55], v[6:7]
	v_mov_b64_e32 v[52:53], v[4:5]
	v_mov_b64_e32 v[50:51], v[2:3]
	v_mov_b64_e32 v[48:49], v[0:1]
	v_mov_b64_e32 v[44:45], v[12:13]
	v_mov_b64_e32 v[42:43], v[10:11]
	v_mov_b64_e32 v[40:41], v[8:9]
	v_mov_b64_e32 v[38:39], v[6:7]
	v_mov_b64_e32 v[36:37], v[4:5]
	v_mov_b64_e32 v[34:35], v[2:3]
	v_mov_b64_e32 v[32:33], v[0:1]
	v_mov_b64_e32 v[28:29], v[12:13]
	v_mov_b64_e32 v[26:27], v[10:11]
	v_mov_b64_e32 v[24:25], v[8:9]
	v_mov_b64_e32 v[22:23], v[6:7]
	v_mov_b64_e32 v[20:21], v[4:5]
	v_mov_b64_e32 v[18:19], v[2:3]
	v_mov_b64_e32 v[16:17], v[0:1]
	v_cmp_eq_f32_e64 s[0:1], 0, v182
	s_cmp_eq_u64 s[0:1], exec
	s_cselect_b32 s19, 1, 0
	v_add_u32_e32 v84, 0x6000, v207
	v_add_u32_e32 v168, 0x6000, v210
.LBB0_216:
	s_mul_i32 s0, s9, 0x6000
	s_add_i32 s14, s0, 0
	s_lshl_b32 s13, s9, 14
	s_add_i32 s16, s14, s6
	s_add_i32 s17, s7, s13
	s_add_i32 s18, s14, s8
	s_mov_b32 s13, s10
	s_mov_b32 s10, s15
	s_mul_i32 s0, s13, 0x6000
	s_add_i32 s0, s0, 0
	s_setprio 1
	ds_read_b128 v[80:83], v84
	ds_read_b128 v[84:87], v84 offset:8192
	ds_read_b128 v[196:199], v168
	ds_read_b128 v[168:171], v168 offset:8192
	v_add_u32_e32 v184, s0, v218
	s_waitcnt lgkmcnt(0)
	v_mfma_f32_32x32x16_bf16 v[96:111], v[80:83], v[156:159], 0
	v_mfma_f32_32x32x16_bf16 v[80:95], v[84:87], v[156:159], 0
	v_mfma_f32_32x32x16_bf16 v[96:111], v[196:199], v[152:155], v[96:111]
	v_mfma_f32_32x32x16_bf16 v[80:95], v[168:171], v[152:155], v[80:95]
	ds_read_b128 v[168:171], v184
	ds_read_b128 v[196:199], v184 offset:8192
	v_add_u32_e32 v184, s0, v221
	s_mov_b32 m0, s16
	s_add_u32 s100, s72, 0x26500000
	s_addc_u32 s101, s73, 0
	global_load_lds_dwordx4 v178, s[100:101]
	s_waitcnt lgkmcnt(0)
	v_mfma_f32_32x32x16_bf16 v[96:111], v[168:171], v[148:151], v[96:111]
	v_mfma_f32_32x32x16_bf16 v[80:95], v[196:199], v[148:151], v[80:95]
	ds_read_b128 v[168:171], v184
	ds_read_b128 v[196:199], v184 offset:8192
	v_add_u32_e32 v184, s0, v222
	s_waitcnt lgkmcnt(0)
	v_mfma_f32_32x32x16_bf16 v[96:111], v[168:171], v[144:147], v[96:111]
	v_mfma_f32_32x32x16_bf16 v[80:95], v[196:199], v[144:147], v[80:95]
	ds_read_b128 v[168:171], v184
	ds_read_b128 v[196:199], v184 offset:8192
	v_add_u32_e32 v184, s0, v223
	s_add_i32 m0, s16, 0x400
	s_nop 0
	global_load_lds_dwordx4 v180, s[100:101]
	s_waitcnt lgkmcnt(0)
	v_mfma_f32_32x32x16_bf16 v[96:111], v[168:171], v[140:143], v[96:111]
	v_mfma_f32_32x32x16_bf16 v[80:95], v[196:199], v[140:143], v[80:95]
	ds_read_b128 v[168:171], v184
	ds_read_b128 v[196:199], v184 offset:8192
	v_add_u32_e32 v184, s0, v224
	v_exp_f32_e32 v233, v73
	s_waitcnt lgkmcnt(0)
	v_mfma_f32_32x32x16_bf16 v[96:111], v[168:171], v[136:139], v[96:111]
	v_mfma_f32_32x32x16_bf16 v[80:95], v[196:199], v[136:139], v[80:95]
	ds_read_b128 v[168:171], v184
	ds_read_b128 v[196:199], v184 offset:8192
	v_add_u32_e32 v184, s0, v225
	s_mov_b32 m0, s17
	s_add_u32 s100, s72, 0x26500100
	s_addc_u32 s101, s73, 0
	global_load_lds_dwordx4 v176, s[100:101]
	v_exp_f32_e32 v250, v74
	s_waitcnt lgkmcnt(0)
	v_mfma_f32_32x32x16_bf16 v[96:111], v[168:171], v[132:135], v[96:111]
	v_mfma_f32_32x32x16_bf16 v[80:95], v[196:199], v[132:135], v[80:95]
	ds_read_b128 v[168:171], v184
	ds_read_b128 v[196:199], v184 offset:8192
	v_add_u32_e32 v184, s0, v226
	v_exp_f32_e32 v200, v75
	s_waitcnt lgkmcnt(0)
	v_mfma_f32_32x32x16_bf16 v[96:111], v[168:171], v[128:131], v[96:111]
	v_mfma_f32_32x32x16_bf16 v[80:95], v[196:199], v[128:131], v[80:95]
	ds_read_b128 v[168:171], v184 offset:16384
	ds_read_b128 v[196:199], v184 offset:20480
	v_add_u32_e32 v184, s0, v227
	s_add_i32 m0, s17, 0x400
	s_add_u32 s100, s72, 0x26500180
	s_addc_u32 s101, s73, 0
	global_load_lds_dwordx4 v176, s[100:101]
	v_exp_f32_e32 v195, v76
	s_waitcnt lgkmcnt(0)
; __device__ __forceinline__ void finishSM(f32x16& p0, f32x16& p1, float alpha, float& l_reg, bf16x8& pa0, bf16x8& pa1, bf16x8& pa2, bf16x8& pa3) {
; #pragma unroll
;     for (int r = 0; r < 16; ++r) p1[r] = __builtin_amdgcn_exp2f(p1[r]);
;     float ps = 0;
; #pragma unroll
;     for (int r = 0; r < 16; ++r) ps += p0[r];
; #pragma unroll
;     for (int r = 0; r < 16; ++r) ps += p1[r];
;     { auto rr = __builtin_amdgcn_permlane32_swap(__float_as_uint(ps), __float_as_uint(ps), false, false);
;       ps = __uint_as_float(rr[0]) + __uint_as_float(rr[1]); }
;     l_reg = l_reg * alpha + ps;
;     ...
;     PK4(p0, 0, pa0); PK4(p0, 8, pa1); PK4(p1, 0, pa2); PK4(p1, 8, pa3);
;     ...
; }
; __device__ __forceinline__ void qkt(f32x16& p0, f32x16& p1, const char* Kn, const bf16x8* qr, int r32, int hi) {
;     const char* Kr = Kn + KR_OFF;
;     p0 = f32x16{}; p1 = f32x16{};
;     __builtin_amdgcn_s_setprio(1);
; #pragma unroll
;     for (int d0 = 0; d0 < 8; ++d0) { const int cb = (d0 * 16 + hi * 8) * 2;
;         const bf16x8 b0 = *reinterpret_cast<const bf16x8*>(Kn + KNSWZ(r32, cb));
;         const bf16x8 b1 = *reinterpret_cast<const bf16x8*>(Kn + KNSWZ(32 + r32, cb));
;         p0 = __builtin_amdgcn_mfma_f32_32x32x16_bf16(b0, qr[d0], p0, 0, 0, 0);
;         p1 = __builtin_amdgcn_mfma_f32_32x32x16_bf16(b1, qr[d0], p1, 0, 0, 0); }
; #pragma unroll
;     for (int d0 = 0; d0 < 4; ++d0) { const int cb = (d0 * 16 + hi * 8) * 2;
;         const bf16x8 b0 = *reinterpret_cast<const bf16x8*>(Kr + KRSWZ(r32, cb));
;         const bf16x8 b1 = *reinterpret_cast<const bf16x8*>(Kr + KRSWZ(32 + r32, cb));
;         p0 = __builtin_amdgcn_mfma_f32_32x32x16_bf16(b0, qr[8 + d0], p0, 0, 0, 0);
;         p1 = __builtin_amdgcn_mfma_f32_32x32x16_bf16(b1, qr[8 + d0], p1, 0, 0, 0); }
; }
; __device__ __forceinline__ int v_st(int k, int c) { const int kk = (k & ~0xC) | ((k & 4) << 1) | ((k & 8) >> 1); return ((kk >> 3) * 4 + (c >> 5)) * 512 + ((kk & 7) * 32 + (c & 31)) * 2; }
; __device__ __forceinline__ int v_rd_base(int lane) { return ((lane & 3) << 3) | (((lane >> 2) & 3) << 6) | (((lane >> 4) & 1) << 5) | (((lane >> 5) & 1) << 8); }
; template <int OFF> __device__ __forceinline__ s16x4 tr_read(int vb) {
;     s16x4 r; asm volatile("ds_read_b64_tr_b16 %0, %1 offset:%2" : "=&v"(r) : "v"(vb), "i"(OFF) : "memory"); return r;
; }
	v_mfma_f32_32x32x16_bf16 v[96:111], v[168:171], v[124:127], v[96:111]
	v_mfma_f32_32x32x16_bf16 v[80:95], v[196:199], v[124:127], v[80:95]
	ds_read_b128 v[168:171], v184 offset:16384
	ds_read_b128 v[196:199], v184 offset:20480
	v_add_u32_e32 v184, s0, v228
	v_exp_f32_e32 v172, v77
	s_waitcnt lgkmcnt(0)
	v_mfma_f32_32x32x16_bf16 v[96:111], v[168:171], v[120:123], v[96:111]
	v_mfma_f32_32x32x16_bf16 v[80:95], v[196:199], v[120:123], v[80:95]
	ds_read_b128 v[168:171], v184 offset:16384
	ds_read_b128 v[196:199], v184 offset:20480
	v_add_u32_e32 v184, s0, v229
	s_add_i32 m0, s18, 0x4000
	s_add_u32 s100, s72, 0x21204000
	s_addc_u32 s101, s73, 0
	global_load_lds_dwordx4 v174, s[100:101]
	v_exp_f32_e32 v173, v78
	s_waitcnt lgkmcnt(0)
	v_mfma_f32_32x32x16_bf16 v[96:111], v[168:171], v[116:119], v[96:111]
	v_mfma_f32_32x32x16_bf16 v[80:95], v[196:199], v[116:119], v[80:95]
	ds_read_b128 v[168:171], v184 offset:16384
	ds_read_b128 v[196:199], v184 offset:20480
	v_exp_f32_e32 v184, v68
	v_exp_f32_e32 v79, v79
	s_waitcnt lgkmcnt(0)
	v_mfma_f32_32x32x16_bf16 v[96:111], v[168:171], v[112:115], v[96:111]
	v_exp_f32_e32 v168, v64
	v_add_f32_e32 v64, 0, v247
	v_add_f32_e32 v64, v249, v64
	v_add_f32_e32 v64, v245, v64
	v_add_f32_e32 v64, v248, v64
	v_add_f32_e32 v64, v244, v64
	v_add_f32_e32 v64, v246, v64
	v_add_f32_e32 v64, v242, v64
	v_add_f32_e32 v64, v243, v64
	v_add_f32_e32 v64, v239, v64
	v_add_f32_e32 v64, v241, v64
	v_add_f32_e32 v64, v238, v64
	v_add_f32_e32 v64, v240, v64
	v_add_f32_e32 v64, v235, v64
	v_exp_f32_e32 v169, v65
	v_add_f32_e32 v64, v237, v64
	v_exp_f32_e32 v170, v66
	v_add_f32_e32 v64, v234, v64
	v_exp_f32_e32 v171, v67
	v_add_f32_e32 v64, v236, v64
	v_add_f32_e32 v64, v168, v64
	v_mfma_f32_32x32x16_bf16 v[80:95], v[196:199], v[112:115], v[80:95]
	v_exp_f32_e32 v196, v69
	v_add_f32_e32 v64, v169, v64
	v_exp_f32_e32 v197, v70
	v_add_f32_e32 v64, v170, v64
	v_exp_f32_e32 v198, v71
	v_add_f32_e32 v64, v171, v64
	v_exp_f32_e32 v199, v72
	v_add_f32_e32 v64, v184, v64
	v_add_f32_e32 v64, v196, v64
	v_add_f32_e32 v64, v197, v64
	v_add_f32_e32 v64, v198, v64
	v_add_f32_e32 v64, v199, v64
	v_add_f32_e32 v64, v233, v64
	v_add_f32_e32 v64, v250, v64
	v_add_f32_e32 v64, v200, v64
	v_add_f32_e32 v64, v195, v64
	v_add_f32_e32 v64, v172, v64
	v_add_f32_e32 v64, v173, v64
	v_add_f32_e32 v231, v79, v64
	v_mov_b32_e32 v232, v231
	v_cvt_pk_bf16_f32 v64, v247, v249
	v_cvt_pk_bf16_f32 v65, v245, v248
	v_cvt_pk_bf16_f32 v66, v244, v246
	s_nop 1
	v_permlane32_swap_b32_e32 v231, v232
	v_cvt_pk_bf16_f32 v67, v242, v243
	v_permlane32_swap_b32_e32 v64, v66
	v_cvt_pk_bf16_f32 v68, v239, v241
	v_cvt_pk_bf16_f32 v69, v238, v240
	v_cvt_pk_bf16_f32 v70, v235, v237
	v_cvt_pk_bf16_f32 v71, v234, v236
	v_cvt_pk_bf16_f32 v72, v168, v169
	v_cvt_pk_bf16_f32 v73, v170, v171
	v_cvt_pk_bf16_f32 v74, v184, v196
	v_cvt_pk_bf16_f32 v75, v197, v198
	v_cvt_pk_bf16_f32 v76, v199, v233
	v_cvt_pk_bf16_f32 v77, v250, v200
	v_cvt_pk_bf16_f32 v78, v195, v172
	v_cvt_pk_bf16_f32 v79, v173, v79
	s_lshl_b32 s15, s15, 14
	v_add_u32_e32 v172, s15, v205
	ds_read_b64_tr_b16 v[168:169], v172 offset:0
	ds_read_b64_tr_b16 v[170:171], v172 offset:0x800
	ds_read_b64_tr_b16 v[196:197], v172 offset:0x1000
	ds_read_b64_tr_b16 v[198:199], v172 offset:0x1800
	ds_read_b64_tr_b16 v[234:235], v172 offset:0x2000
	ds_read_b64_tr_b16 v[236:237], v172 offset:0x2800
	ds_read_b64_tr_b16 v[238:239], v172 offset:0x3000
	ds_read_b64_tr_b16 v[240:241], v172 offset:0x3800
	v_permlane32_swap_b32_e32 v65, v67
	v_permlane32_swap_b32_e32 v68, v70
	v_permlane32_swap_b32_e32 v69, v71
	v_permlane32_swap_b32_e32 v72, v74
	v_permlane32_swap_b32_e32 v73, v75
	v_permlane32_swap_b32_e32 v76, v78
	v_permlane32_swap_b32_e32 v77, v79
	s_setprio 0
	s_waitcnt lgkmcnt(0)
	s_nop 0
	v_mfma_f32_32x32x16_bf16 v[0:15], v[64:67], v[168:171], v[0:15]
	ds_read_b64_tr_b16 v[168:169], v172 offset:0x200
	ds_read_b64_tr_b16 v[170:171], v172 offset:0xa00
	v_mfma_f32_32x32x16_bf16 v[0:15], v[68:71], v[196:199], v[0:15]
	ds_read_b64_tr_b16 v[196:197], v172 offset:0x1200
	ds_read_b64_tr_b16 v[198:199], v172 offset:0x1a00
	v_mfma_f32_32x32x16_bf16 v[0:15], v[72:75], v[234:237], v[0:15]
	ds_read_b64_tr_b16 v[234:235], v172 offset:0x2200
	ds_read_b64_tr_b16 v[236:237], v172 offset:0x2a00
	v_mfma_f32_32x32x16_bf16 v[0:15], v[76:79], v[238:241], v[0:15]
	ds_read_b64_tr_b16 v[238:239], v172 offset:0x3200
	ds_read_b64_tr_b16 v[240:241], v172 offset:0x3a00
	s_waitcnt lgkmcnt(0)
	v_mfma_f32_32x32x16_bf16 v[48:63], v[64:67], v[168:171], v[48:63]
	ds_read_b64_tr_b16 v[168:169], v172 offset:0x400
	ds_read_b64_tr_b16 v[170:171], v172 offset:0xc00
	v_mfma_f32_32x32x16_bf16 v[48:63], v[68:71], v[196:199], v[48:63]
	ds_read_b64_tr_b16 v[196:197], v172 offset:0x1400
	ds_read_b64_tr_b16 v[198:199], v172 offset:0x1c00
	v_mfma_f32_32x32x16_bf16 v[48:63], v[72:75], v[234:237], v[48:63]
	ds_read_b64_tr_b16 v[234:235], v172 offset:0x2400
	ds_read_b64_tr_b16 v[236:237], v172 offset:0x2c00
	v_mfma_f32_32x32x16_bf16 v[48:63], v[76:79], v[238:241], v[48:63]
	ds_read_b64_tr_b16 v[238:239], v172 offset:0x3400
	ds_read_b64_tr_b16 v[240:241], v172 offset:0x3c00
	s_waitcnt lgkmcnt(0)
	v_mfma_f32_32x32x16_bf16 v[32:47], v[64:67], v[168:171], v[32:47]
	ds_read_b64_tr_b16 v[168:169], v172 offset:0x600
	ds_read_b64_tr_b16 v[170:171], v172 offset:0xe00
	v_mfma_f32_32x32x16_bf16 v[32:47], v[68:71], v[196:199], v[32:47]
	ds_read_b64_tr_b16 v[196:197], v172 offset:0x1600
	ds_read_b64_tr_b16 v[198:199], v172 offset:0x1e00
	v_mfma_f32_32x32x16_bf16 v[32:47], v[72:75], v[234:237], v[32:47]
	ds_read_b64_tr_b16 v[234:235], v172 offset:0x2600
	ds_read_b64_tr_b16 v[236:237], v172 offset:0x2e00
	v_mfma_f32_32x32x16_bf16 v[32:47], v[76:79], v[238:241], v[32:47]
	ds_read_b64_tr_b16 v[238:239], v172 offset:0x3600
	ds_read_b64_tr_b16 v[240:241], v172 offset:0x3e00
	s_waitcnt lgkmcnt(0)
	v_mfma_f32_32x32x16_bf16 v[16:31], v[64:67], v[168:171], v[16:31]
	v_max_f32_e32 v64, v97, v97
	v_max_f32_e32 v65, v96, v96
	v_max_f32_e32 v64, v65, v64
	v_max3_f32 v64, v64, v98, v99
	v_max3_f32 v64, v64, v100, v101
	v_max3_f32 v64, v64, v102, v103
	v_max3_f32 v64, v64, v104, v105
	v_mfma_f32_32x32x16_bf16 v[16:31], v[68:71], v[196:199], v[16:31]
	v_max3_f32 v64, v64, v106, v107
	v_max3_f32 v64, v64, v108, v109
	v_max3_f32 v64, v64, v110, v111
	v_max3_f32 v64, v64, v80, v81
	v_max3_f32 v64, v64, v82, v83
	v_max3_f32 v64, v64, v84, v85
	v_max3_f32 v64, v64, v86, v87
	v_mfma_f32_32x32x16_bf16 v[16:31], v[72:75], v[234:237], v[16:31]
	v_max3_f32 v64, v64, v88, v89
	v_max3_f32 v64, v64, v90, v91
	v_max3_f32 v64, v64, v92, v93
	v_max3_f32 v64, v64, v94, v95
	v_mov_b32_e32 v65, v64
	s_nop 1
	v_permlane32_swap_b32_e32 v64, v65
	v_max_f32_e32 v65, v65, v65
	v_max_f32_e32 v64, v64, v64
	v_mfma_f32_32x32x16_bf16 v[16:31], v[76:79], v[238:241], v[16:31]
	v_max_f32_e32 v64, v64, v65
	v_sub_f32_e32 v65, v64, v182
	s_mov_b32 s0, 0x41300000
	v_cmp_ge_f32_e32 vcc, s0, v65
	v_mov_b32_e32 v184, v182
	v_mov_b32_e32 v233, 1.0
	s_cmp_eq_u64 vcc, exec
	s_cbranch_scc0 .Latt_slow1
; template <bool FIRST>
; __device__ __forceinline__ void partialSM(f32x16& p0, f32x16& p1, float& m_reg, float& mn, float& alpha) {
;     ...
;     else if (__builtin_expect(__all(pmax - m_reg <= THRL), 1)) { mn = m_reg; alpha = 1.f; }
;     else { mn = fmaxf(m_reg, pmax); alpha = __builtin_amdgcn_exp2f(m_reg - mn); m_reg = mn; }
;     if (!__builtin_expect(__all(mn == 0.f), 1)) {
; #pragma unroll
;         for (int r = 0; r < 16; ++r) p0[r] = p0[r] - mn;
; #pragma unroll
;         for (int r = 0; r < 16; ++r) p1[r] = p1[r] - mn; }
	s_cmp_lg_u32 s19, 0
	s_cbranch_scc0 .LBB0_228

; #define SBAR() __builtin_amdgcn_sched_barrier(0)
; #define WAIT_BAR() asm volatile("s_waitcnt vmcnt(0) lgkmcnt(0)\n\ts_barrier" ::: "memory")
; #define RESC(a) do { if (__any((a) < 1.f)) { if (hi == 0) al_l[r32] = (a); asm volatile("s_waitcnt lgkmcnt(0)" ::: "memory"); \
;     _Pragma("unroll") for (int d = 0; d < 4; ++d) _Pragma("unroll") for (int r = 0; r < 16; ++r) o[d][r] *= al_l[crow(r, hi)]; } } while (0)
; #define ROT() do { const int t_ = s_prev; s_prev = s_cur; s_cur = s_next; s_next = t_; } while (0)
; __device__ __forceinline__ void finishSM(f32x16& p0, f32x16& p1, float alpha, float& l_reg, bf16x8& pa0, bf16x8& pa1, bf16x8& pa2, bf16x8& pa3) {
;     ...
;     l_reg = l_reg * alpha + ps;
; __device__ __forceinline__ void attn_unit(const bf16_t* __restrict__ Qb, const bf16_t* __restrict__ Kn, const bf16_t* __restrict__ Vh, const bf16_t* __restrict__ Kr,
;                                           bf16_t* __restrict__ Ob, int seq, char* lds, int wv_) { LAUNDER_IDS;
;     ...
;     for (int j = 1; j + 1 < NT; j += 2) {
;         DMA(j + 1, s_next); SBAR();
;         qkt(pB0, pB1, lds + OFF_K + s_cur * SLOT_K, qr, r32, hi);
;         finishSM(pA0, pA1, alA, l_reg, pa0, pa1, pa2, pa3); __builtin_amdgcn_s_setprio(0); SBAR();
;         pv_d0(o, vb0 + s_prev * SLOT_V, pa0, pa1, pa2, pa3); partialSM<false>(pB0, pB1, m_reg, mnB, alB);
;         RESC(alB); WAIT_BAR(); ROT();
;         DMA(j + 2, s_next); SBAR();
;         qkt(pA0, pA1, lds + OFF_K + s_cur * SLOT_K, qr, r32, hi);
;         finishSM(pB0, pB1, alB, l_reg, pa0, pa1, pa2, pa3); __builtin_amdgcn_s_setprio(0); SBAR();
;         pv_d0(o, vb0 + s_prev * SLOT_V, pa0, pa1, pa2, pa3); partialSM<false>(pA0, pA1, m_reg, mnA, alA);
;         RESC(alA); WAIT_BAR(); ROT();
;     }
.LBB0_226:
	v_exp_f32_e32 v247, v96
	v_exp_f32_e32 v249, v97
	v_exp_f32_e32 v245, v98
	v_exp_f32_e32 v248, v99
	v_exp_f32_e32 v244, v100
	v_exp_f32_e32 v246, v101
	v_exp_f32_e32 v242, v102
	v_exp_f32_e32 v243, v103
	v_exp_f32_e32 v239, v104
	v_exp_f32_e32 v241, v105
	v_exp_f32_e32 v238, v106
	v_exp_f32_e32 v240, v107
	v_exp_f32_e32 v235, v108
	v_exp_f32_e32 v237, v109
	v_exp_f32_e32 v234, v110
	v_exp_f32_e32 v236, v111
	v_add_f32_e32 v82, v231, v232
	s_mov_b64 s[0:1], 0x4000
	v_fmac_f32_e32 v82, v230, v203
	v_add_f32_e32 v203, v80, v81
	s_add_i32 s11, s11, 2
	v_lshl_add_u64 v[174:175], v[174:175], 0, s[0:1]
	s_mov_b64 s[0:1], 0x100000
	v_fmac_f32_e32 v203, v82, v233
	v_lshl_add_u64 v[176:177], v[176:177], 0, s[0:1]
	v_lshl_add_u64 v[178:179], v[178:179], 0, s[0:1]
	v_lshl_add_u64 v[180:181], v[180:181], 0, s[0:1]
	v_mov_b32_e32 v230, v184
	s_mul_i32 s17, s10, 0x6000
	v_add_u32_e32 v84, s17, v207
	v_add_u32_e32 v168, s17, v210
	s_waitcnt vmcnt(0) lgkmcnt(0)
	s_barrier
	s_cmpk_gt_u32 s11, 0x7c
	s_cbranch_scc1 .LBB0_230
	s_mov_b32 s15, s9
	s_mov_b32 s9, s13
	s_branch .LBB0_216
